# prompt attention: K tiles fetched quad-contiguously (16 requests per load instead of 64), own LDS store offset for K
# baseline (speedup 1.0000x reference)
; #define LAS __attribute__((address_space(3)))
; template <bool FIXED> __device__ __forceinline__ void attn_prompt_unit(const Params& P, const Ctx& C, int bg, int qb) {
;     ...
;     const int lane = lane_, wave = C.wave, r32 = lane & 31, hi = lane >> 5;
;     const int b = bg >> 2, g = bg & 3, qi = r32 & 15, hsel = r32 >> 4, hq = 2 * g + hsel;
;     const int t = 128 * qb + 16 * wave + qi;
;     const size_t row = (size_t)b * SEQ + t;
;     bf16x8 qr[4];
;     { const bf16_t* qp = (const bf16_t*)(ws + WS_Q) + row * 512 + hq * 64 + hi * 8;
; #pragma unroll
;       for (int d0 = 0; d0 < 4; ++d0) qr[d0] = *(const bf16x8*)(qp + d0 * 16); }
;     LAS unsigned char* KB = C.lds + AT_KB; LAS unsigned char* VB = C.lds + AT_VB;
;     LAS float* IMP = (LAS float*)(C.lds + AT_IMP) + wave * 2048; LAS unsigned* SELM = (LAS unsigned*)(C.lds + AT_SEL) + wave * 64;
;     const float* gts = (const float*)(ws + WS_GATES) + row * 24 + hq * 3;
;     const float g0 = gts[0], g1 = gts[1], g2 = gts[2];
;     f32x16 oa0, oa1, s0, s1;
;     u32x4 kr, vr, kr2, vr2;
;     const int t0 = 128 * qb + 16 * wave;
;     f32x16 nm;
;     {
;         const int ntc = (qb >> 3) + 1, cmax = (t >= 31) ? ((t - 31) >> 4) : -1, cmin_w = (t0 >= 31) ? ((t0 - 31) >> 4) : -1;
;         const bf16_t* kcb = (const bf16_t*)(ws + WS_KCC) + (size_t)bg * 512 * 64; const bf16_t* vcb = (const bf16_t*)(ws + WS_VCC) + (size_t)bg * 512 * 64;
;         float m_c = -1e30f, l_c = 0.f; nm = (f32x16)F16Z;
;         __syncthreads();
;         tile_ld(kcb, vcb, wave, lane, kr, vr);
;         for (int j = 0; j < ntc; ++j) {
;             tile_st(KB + (j & 1) * 8192, VB + (j & 1) * 8192, wave, lane, kr, vr);
;             __syncthreads();
;             if (j + 1 < ntc) tile_ld(kcb + (size_t)(j + 1) * 4096, vcb + (size_t)(j + 1) * 4096, wave, lane, kr, vr);
.LBB0_1510:
	s_and_b64 vcc, exec, s[2:3]
	s_cbranch_vccz .LBB0_1200
	s_mov_b64 s[12:13], s[58:59]
	s_waitcnt vmcnt(8)
	v_mbcnt_lo_u32_b32 v127, -1, 0
	v_mbcnt_hi_u32_b32 v127, -1, v127
	v_readlane_b32 s2, v255, 55
	v_and_b32_e32 v148, 15, v127
	v_bfe_u32 v126, v127, 4, 1
	v_or_b32_e32 v10, s2, v126
	v_or_b32_e32 v171, s30, v148
	v_readlane_b32 s2, v255, 56
	v_ashrrev_i32_e32 v131, 5, v127
	v_lshlrev_b32_e32 v4, 7, v10
	v_add_u32_e32 v0, s2, v171
	v_lshlrev_b64 v[2:3], 10, v[0:1]
	v_lshl_add_u64 v[2:3], s[12:13], 0, v[2:3]
	v_mov_b32_e32 v5, v1
	v_lshl_add_u64 v[2:3], v[2:3], 0, v[4:5]
	v_lshlrev_b32_e32 v4, 3, v131
	v_ashrrev_i32_e32 v5, 31, v4
	v_lshl_add_u64 v[2:3], v[4:5], 1, v[2:3]
	s_mov_b64 s[2:3], 0x6c00000
	v_lshl_add_u64 v[4:5], v[2:3], 0, s[2:3]
	s_mov_b32 s2, 0x6c00000
	v_add_co_u32_e32 v2, vcc, s2, v2
	s_movk_i32 s2, 0x60
	s_nop 0
	v_addc_co_u32_e32 v3, vcc, 0, v3, vcc
	global_load_dwordx4 v[82:85], v[4:5], off offset:32
	global_load_dwordx4 v[86:89], v[4:5], off offset:64
	global_load_dwordx4 v[90:93], v[2:3], off
	global_load_dwordx4 v[94:97], v[4:5], off offset:96
	v_mov_b64_e32 v[2:3], s[12:13]
	v_mul_u32_u24_e32 v4, 3, v10
	v_mad_u64_u32 v[2:3], s[2:3], v0, s2, v[2:3]
	v_lshlrev_b32_e32 v4, 2, v4
	v_mov_b32_e32 v5, v1
	v_lshl_add_u64 v[2:3], v[2:3], 0, v[4:5]
	s_mov_b32 s2, 0x2500000
	v_add_co_u32_e32 v2, vcc, s2, v2
	s_sub_i32 s2, s30, 31
	s_lshr_b32 s18, s64, 3
	s_ashr_i32 s2, s2, 4
	s_cmp_gt_i32 s30, 30
	s_cselect_b32 s19, s2, -1
	v_readlane_b32 s2, v255, 57
	s_lshl_b32 s2, s2, 1
	s_add_u32 s2, s12, s2
	v_readlane_b32 s98, v254, 6
	v_bfe_u32 v203, v127, 2, 3
	v_lshrrev_b32_e32 v204, 5, v127
	v_and_b32_e32 v205, 3, v127
	v_lshlrev_b32_e32 v142, 7, v203
	v_lshl_add_u32 v142, v204, 6, v142
	v_lshl_add_u32 v142, v205, 4, v142
	s_mul_i32 s99, s98, 1008
	v_add_u32_e32 v142, s99, v142
	v_lshl_add_u32 v202, v204, 2, v205
	v_lshlrev_b32_e32 v202, 10, v202
	v_lshl_add_u32 v202, v203, 4, v202
	s_mul_i32 s99, s98, 896
	v_subrev_u32_e32 v202, s99, v202
	v_ashrrev_i32_e32 v128, 2, v127
	v_addc_co_u32_e32 v3, vcc, 0, v3, vcc
	s_addc_u32 s3, s13, 0
	v_ashrrev_i32_e32 v143, 31, v142
	v_add_lshl_u32 v144, v128, s73, 7
	global_load_dwordx3 v[168:170], v[2:3], off
	v_lshl_add_u64 v[2:3], s[2:3], 0, v[142:143]
	v_ashrrev_i32_e32 v145, 31, v144
	v_lshl_add_u64 v[2:3], v[2:3], 0, s[66:67]
	s_mov_b32 s4, 0x36e00000
	v_lshl_add_u64 v[6:7], s[2:3], 0, v[144:145]
	v_lshlrev_b32_e32 v173, 4, v127
	v_add_co_u32_e32 v4, vcc, s4, v2
	v_lshl_add_u64 v[6:7], v[6:7], 0, s[68:69]
	v_and_b32_e32 v146, 48, v173
	v_mov_b32_e32 v147, v1
	v_addc_co_u32_e32 v5, vcc, 0, v3, vcc
	v_lshl_add_u64 v[6:7], v[6:7], 0, v[146:147]
	s_mov_b32 s2, 0x37700000
	v_add_co_u32_e32 v8, vcc, s2, v6
	s_barrier
	s_nop 0
	v_addc_co_u32_e32 v9, vcc, 0, v7, vcc
	global_load_dwordx4 v[98:101], v[4:5], off
	global_load_dwordx4 v[102:105], v[8:9], off
	v_subrev_u32_e32 v4, 31, v171
	v_ashrrev_i32_e32 v4, 4, v4
	v_cmp_lt_i32_e32 vcc, 30, v171
	s_mov_b64 s[2:3], 0x36e00000
	v_and_b32_e32 v132, 31, v127
	v_cndmask_b32_e32 v129, -1, v4, vcc
	v_lshl_add_u64 v[122:123], v[2:3], 0, s[2:3]
	s_mov_b64 s[2:3], 0x37700000
	v_lshlrev_b32_e32 v172, 6, v10
	s_mov_b32 s10, 0
	v_lshl_add_u64 v[124:125], v[6:7], 0, s[2:3]
	v_add_u32_e32 v133, s82, v173
	v_subrev_u32_e32 v130, 32, v129
	v_lshlrev_b32_e32 v175, 10, v131
	v_lshlrev_b32_e32 v184, 4, v132
	v_lshlrev_b32_e32 v174, 2, v131
	s_add_i32 s20, s18, 1
	v_mov_b32_e32 v34, v1
	v_mov_b32_e32 v35, v1
	v_mov_b32_e32 v36, v1
	v_mov_b32_e32 v37, v1
	v_mov_b32_e32 v38, v1
	v_mov_b32_e32 v39, v1
	v_mov_b32_e32 v40, v1
	v_mov_b32_e32 v41, v1
	v_mov_b32_e32 v42, v1
	v_mov_b32_e32 v43, v1
	v_mov_b32_e32 v44, v1
	v_mov_b32_e32 v45, v1
	v_mov_b32_e32 v46, v1
	v_mov_b32_e32 v47, v1
	v_mov_b32_e32 v48, v1
	v_mov_b32_e32 v49, v1
	v_mov_b32_e32 v135, 0xf149f2ca
	v_mov_b32_e32 v134, 0
	s_mov_b32 s11, 63
	s_mov_b64 s[2:3], 0x1000
	s_mov_b32 s14, 0
; #define LAS __attribute__((address_space(3)))
; __device__ __forceinline__ float fast_exp2(float x) { return __builtin_amdgcn_exp2f(x); }
; #define MFMA32(a, b, c) __builtin_amdgcn_mfma_f32_32x32x16_bf16(a, b, c, 0, 0, 0)
; template <bool EMASK, bool DO_PV> ...
;     const LAS unsigned char* kp = kb + hi * 1024 + r32 * 16;
;     a = nm; b = nm;
; #pragma unroll
;     for (int d0 = 0; d0 < 4; ++d0) {
;         const bf16x8 k0 = *(const LAS bf16x8*)(kp + d0 * 2048), k1 = *(const LAS bf16x8*)(kp + d0 * 2048 + 512);
;         a = MFMA32(k0, qr[d0], a); b = MFMA32(k1, qr[d0], b);
;     }
;     if (EMASK) mask_tile(a, b, key0, klo, khi, true, hi);
;     float mx = tile_max(a, b); mx = en ? mx : NEG_INF;
;     const bool unset = m < -1e29f;
;     const bool need = unset ? (mx > NEG_INF) : (mx > ATT_THR);
;     if (__any(need)) {
;         const float d = unset ? (need ? mx : 0.f) : fmaxf(mx, 0.f);
;         const float al = unset ? 1.f : fast_exp2(-d);
;         m = unset ? (need ? mx : m) : m + d;
;         l *= al; if (DO_PV) { o0 = o0 * al; o1 = o1 * al; }
;         nm = nm - d; a = a - d; b = b - d;
;     }
; template <bool FIXED> __device__ __forceinline__ void attn_prompt_unit(const Params& P, const Ctx& C, int bg, int qb) {
;     ...
;         for (int j = 0; j < ntc; ++j) {
;             tile_st(KB + (j & 1) * 8192, VB + (j & 1) * 8192, wave, lane, kr, vr);
;             __syncthreads();
;             if (j + 1 < ntc) tile_ld(kcb + (size_t)(j + 1) * 4096, vcb + (size_t)(j + 1) * 4096, wave, lane, kr, vr);
;             else tile_ld(kcb, vcb, wave, lane, kr, vr);
;             if (64 * j + 63 <= cmin_w) att_step<false, false>(KB + (j & 1) * 8192, VB, qr, m_c, l_c, nm, s0, s1, s0, s1, 64 * j, 0, cmax, true, lane, r32, hi);
;             else att_step<true, false>(KB + (j & 1) * 8192, VB, qr, m_c, l_c, nm, s0, s1, s0, s1, 64 * j, 0, cmax, true, lane, r32, hi);
.LBB0_1512:
	s_and_b32 s4, s10, 0x2000
	s_add_i32 s6, s4, 0
	s_add_i32 s5, s6, s44
	v_add_u32_e32 v2, s5, v173
	v_add_u32_e32 v203, s5, v202
	s_cmp_lt_u32 s14, s18
	s_waitcnt vmcnt(1)
	ds_write_b128 v203, v[98:101]
	v_add_u32_e32 v2, s4, v133
	s_cselect_b32 s5, s3, 0
	s_cselect_b32 s4, s2, 0
	s_lshl_b64 s[4:5], s[4:5], 1
	v_lshl_add_u64 v[4:5], v[122:123], 0, s[4:5]
	s_waitcnt vmcnt(0)
	ds_write_b128 v2, v[102:105] offset:32768
	s_waitcnt lgkmcnt(0)
	s_barrier
	v_lshl_add_u64 v[2:3], v[124:125], 0, s[4:5]
	global_load_dwordx4 v[98:101], v[4:5], off
	global_load_dwordx4 v[102:105], v[2:3], off
	v_add3_u32 v2, s6, v175, v184
	ds_read_b128 v[114:117], v2
	ds_read_b128 v[118:121], v2 offset:512
	ds_read_b128 v[110:113], v2 offset:2048
	ds_read_b128 v[106:109], v2 offset:2560
	ds_read_b128 v[78:81], v2 offset:4096
	ds_read_b128 v[74:77], v2 offset:4608
	ds_read_b128 v[70:73], v2 offset:6144
	ds_read_b128 v[66:69], v2 offset:6656
	s_cmp_gt_i32 s11, s19
	s_mov_b64 s[6:7], -1
	v_cmp_gt_f32_e64 s[4:5], s1, v135
	s_cbranch_scc1 .LBB0_1516
	s_waitcnt lgkmcnt(7)
	v_mfma_f32_32x32x16_bf16 v[2:17], v[114:117], v[90:93], v[34:49]
	v_mov_b32_e32 v136, v135
	v_mov_b32_e32 v137, v134
	s_waitcnt lgkmcnt(6)
	v_mfma_f32_32x32x16_bf16 v[18:33], v[118:121], v[90:93], v[34:49]
	s_waitcnt lgkmcnt(5)
	v_mfma_f32_32x32x16_bf16 v[2:17], v[110:113], v[82:85], v[2:17]
	s_waitcnt lgkmcnt(4)
	v_mfma_f32_32x32x16_bf16 v[18:33], v[106:109], v[82:85], v[18:33]
	s_waitcnt lgkmcnt(3)
	v_mfma_f32_32x32x16_bf16 v[2:17], v[78:81], v[86:89], v[2:17]
	s_waitcnt lgkmcnt(2)
	v_mfma_f32_32x32x16_bf16 v[18:33], v[74:77], v[86:89], v[18:33]
	s_waitcnt lgkmcnt(0)
	v_mfma_f32_32x32x16_bf16 v[18:33], v[66:69], v[94:97], v[18:33]
	v_mfma_f32_32x32x16_bf16 v[2:17], v[70:73], v[94:97], v[2:17]
	s_nop 10
	v_max_f32_e32 v50, v19, v19
	v_max_f32_e32 v51, v3, v3
	v_max_f32_e32 v50, v51, v50
	v_max_f32_e32 v51, v20, v20
	v_max_f32_e32 v52, v4, v4
	v_max_f32_e32 v51, v52, v51
	v_max_f32_e32 v52, v21, v21
	v_max_f32_e32 v53, v5, v5
	v_max3_f32 v50, v2, v18, v50
	v_max_f32_e32 v52, v53, v52
	v_max3_f32 v50, v50, v51, v52
	v_max_f32_e32 v51, v22, v22
	v_max_f32_e32 v52, v6, v6
	v_max_f32_e32 v51, v52, v51
	v_max_f32_e32 v52, v23, v23
	v_max_f32_e32 v53, v7, v7
	v_max_f32_e32 v52, v53, v52
	v_max3_f32 v50, v50, v51, v52
	v_max_f32_e32 v51, v24, v24
	v_max_f32_e32 v52, v8, v8
	v_max_f32_e32 v51, v52, v51
	v_max_f32_e32 v52, v25, v25
	v_max_f32_e32 v53, v9, v9
	v_max_f32_e32 v52, v53, v52
	v_max3_f32 v50, v50, v51, v52
	v_max_f32_e32 v51, v26, v26
	v_max_f32_e32 v52, v10, v10
	v_max_f32_e32 v51, v52, v51
	v_max_f32_e32 v52, v27, v27
	v_max_f32_e32 v53, v11, v11
	v_max_f32_e32 v52, v53, v52
	v_max3_f32 v50, v50, v51, v52
	v_max_f32_e32 v51, v28, v28
	v_max_f32_e32 v52, v12, v12
	v_max_f32_e32 v51, v52, v51
	v_max_f32_e32 v52, v29, v29
	v_max_f32_e32 v53, v13, v13
	v_max_f32_e32 v52, v53, v52
	v_max3_f32 v50, v50, v51, v52
	v_max_f32_e32 v51, v30, v30
	v_max_f32_e32 v52, v14, v14
	v_max_f32_e32 v51, v52, v51
	v_max_f32_e32 v52, v31, v31
	v_max_f32_e32 v53, v15, v15
	v_max_f32_e32 v52, v53, v52
	v_max3_f32 v50, v50, v51, v52
	v_max_f32_e32 v51, v32, v32
	v_max_f32_e32 v52, v16, v16
	v_max_f32_e32 v51, v52, v51
	v_max_f32_e32 v52, v33, v33
	v_max_f32_e32 v53, v17, v17
	v_max_f32_e32 v52, v53, v52
	v_max3_f32 v50, v50, v51, v52
	v_mov_b32_e32 v51, v50
	s_nop 1
	v_permlane32_swap_b32_e32 v50, v51
	v_max_f32_e32 v51, v51, v51
	v_max_f32_e32 v50, v50, v50
	v_max_f32_e32 v138, v50, v51
	v_cmp_lg_f32_e64 s[6:7], s50, v138
	v_cmp_lt_f32_e32 vcc, s0, v138
	s_nop 0
	v_cndmask_b32_e64 v50, 0, 1, s[6:7]
	v_cndmask_b32_e64 v51, 0, 1, vcc
	v_cndmask_b32_e64 v50, v51, v50, s[4:5]
	v_and_b32_e32 v50, 1, v50
	v_cmp_eq_u32_e64 s[8:9], 1, v50
	v_cmp_ne_u32_e32 vcc, 0, v50
	v_mov_b64_e32 v[64:65], v[48:49]
	v_mov_b64_e32 v[62:63], v[46:47]
	v_mov_b64_e32 v[60:61], v[44:45]
	v_mov_b64_e32 v[58:59], v[42:43]
	v_mov_b64_e32 v[56:57], v[40:41]
	v_mov_b64_e32 v[54:55], v[38:39]
	v_mov_b64_e32 v[52:53], v[36:37]
	v_mov_b64_e32 v[50:51], v[34:35]
	s_cbranch_vccz .LBB0_1515
	v_max_f32_e32 v51, v138, v138
	v_cndmask_b32_e64 v50, 0, v138, s[6:7]
	v_max_f32_e32 v51, 0, v51
	v_cndmask_b32_e64 v139, v51, v50, s[4:5]
	v_exp_f32_e64 v50, -v139
	v_cndmask_b32_e64 v52, v135, v138, s[8:9]
	v_add_f32_e32 v51, v135, v51
	v_cndmask_b32_e64 v136, v51, v52, s[4:5]
	v_cndmask_b32_e64 v50, v50, 1.0, s[4:5]
	v_mul_f32_e32 v137, v134, v50
	v_sub_f32_e32 v65, v49, v139
	v_sub_f32_e32 v64, v48, v139
	v_sub_f32_e32 v63, v47, v139
	v_sub_f32_e32 v62, v46, v139
	v_sub_f32_e32 v61, v45, v139
	v_sub_f32_e32 v60, v44, v139
	v_sub_f32_e32 v59, v43, v139
	v_sub_f32_e32 v58, v42, v139
	v_sub_f32_e32 v57, v41, v139
	v_sub_f32_e32 v56, v40, v139
	v_sub_f32_e32 v55, v39, v139
	v_sub_f32_e32 v54, v38, v139
	v_sub_f32_e32 v53, v37, v139
	v_sub_f32_e32 v52, v36, v139
	v_sub_f32_e32 v51, v35, v139
	v_sub_f32_e32 v50, v34, v139
	v_sub_f32_e32 v2, v2, v139
	v_sub_f32_e32 v3, v3, v139
	v_sub_f32_e32 v4, v4, v139
	v_sub_f32_e32 v5, v5, v139
	v_sub_f32_e32 v6, v6, v139
	v_sub_f32_e32 v7, v7, v139
	v_sub_f32_e32 v8, v8, v139
	v_sub_f32_e32 v9, v9, v139
	v_sub_f32_e32 v10, v10, v139
	v_sub_f32_e32 v11, v11, v139
	v_sub_f32_e32 v12, v12, v139
	v_sub_f32_e32 v13, v13, v139
	v_sub_f32_e32 v14, v14, v139
	v_sub_f32_e32 v15, v15, v139
	v_sub_f32_e32 v16, v16, v139
	v_sub_f32_e32 v17, v17, v139
	v_sub_f32_e32 v18, v18, v139
	v_sub_f32_e32 v19, v19, v139
	v_sub_f32_e32 v20, v20, v139
	v_sub_f32_e32 v21, v21, v139
	v_sub_f32_e32 v22, v22, v139
	v_sub_f32_e32 v23, v23, v139
	v_sub_f32_e32 v24, v24, v139
	v_sub_f32_e32 v25, v25, v139
	v_sub_f32_e32 v26, v26, v139
	v_sub_f32_e32 v27, v27, v139
	v_sub_f32_e32 v28, v28, v139
	v_sub_f32_e32 v29, v29, v139
	v_sub_f32_e32 v30, v30, v139
	v_sub_f32_e32 v31, v31, v139
	v_sub_f32_e32 v32, v32, v139
	v_sub_f32_e32 v33, v33, v139

; template <bool FIXED> __device__ __forceinline__ void attn_prompt_unit(const Params& P, const Ctx& C, int bg, int qb) {
;     ...
;         for (int j = 0; j < ntc; ++j) {
;             tile_st(KB + (j & 1) * 8192, VB + (j & 1) * 8192, wave, lane, kr, vr);
;             __syncthreads();
;             if (j + 1 < ntc) tile_ld(kcb + (size_t)(j + 1) * 4096, vcb + (size_t)(j + 1) * 4096, wave, lane, kr, vr);
;             else { const bf16_t* ks_ = (const bf16_t*)(ws + WS_KS) + (size_t)bg * SEQ * 64; const bf16_t* vs_ = (const bf16_t*)(ws + WS_VS) + (size_t)bg * SEQ * 64;
;                    tile_ld(ks_, vs_, wave, lane, kr, vr); tile_ld(ks_ + 4096, vs_ + 4096, wave, lane, kr2, vr2); }
.LBB0_1523:
	s_and_b32 s8, s16, 0x2000
	s_add_i32 s26, s8, 0
	s_add_i32 s8, s26, s44
	v_add_u32_e32 v58, s8, v173
	v_add_u32_e32 v203, s8, v202
	s_cmp_ge_u32 s22, s18
	s_mov_b64 s[8:9], -1
	s_waitcnt vmcnt(1)
	ds_write_b128 v203, v[98:101]
	s_waitcnt vmcnt(0)
	ds_write_b128 v58, v[102:105] offset:32768
	s_waitcnt lgkmcnt(0)
	s_barrier
	s_cbranch_scc0 .LBB0_1525
	global_load_dwordx4 v[106:109], v[114:115], off
	global_load_dwordx4 v[110:113], v[116:117], off
	s_mov_b64 s[8:9], 0

; #define LAS __attribute__((address_space(3)))
; template <bool FIXED> __device__ __forceinline__ void attn_prompt_unit(const Params& P, const Ctx& C, int bg, int qb) {
;     ...
;         for (int jp = 0; jp <= jl; jp += 2) {
;             LAS unsigned char* kcur = KB + ((jp >> 1) & 1) * 16384; LAS unsigned char* vcur = VB + ((jp >> 1) & 1) * 16384;
;             tile_st(kcur, vcur, wave, lane, kr, vr); tile_st(kcur + 8192, vcur + 8192, wave, lane, kr2, vr2);
;             __syncthreads();
;             if (jp + 2 <= jl) { tile_ld(kb_ + (size_t)(jp + 2) * 4096, vb_ + (size_t)(jp + 2) * 4096, wave, lane, kr, vr); tile_ld(kb_ + (size_t)(jp + 3) * 4096, vb_ + (size_t)(jp + 3) * 4096, wave, lane, kr2, vr2); }
;             else { const int jw_ = (2 * qb - 8 > 0) ? 2 * qb - 8 : 0; const bf16_t* kw_ = (const bf16_t*)(ws + WS_KW) + (size_t)bg * SEQ * 64; const bf16_t* vw_ = (const bf16_t*)(ws + WS_VW) + (size_t)bg * SEQ * 64;
;                    tile_ld(kw_ + (size_t)jw_ * 4096, vw_ + (size_t)jw_ * 4096, wave, lane, kr, vr); tile_ld(kw_ + (size_t)(jw_ + 1) * 4096, vw_ + (size_t)(jw_ + 1) * 4096, wave, lane, kr2, vr2); }
.LBB0_1542:
	s_and_b32 s6, s24, 0x4000
	s_add_i32 s42, s6, 0
	s_add_i32 s6, s42, s44
	s_add_i32 s39, s34, 1
	v_add_u32_e32 v34, s6, v173
	v_add_u32_e32 v203, s6, v202
	s_cmp_gt_u32 s39, s31
	s_mov_b64 s[6:7], s[22:23]
	s_mov_b64 s[8:9], s[20:21]
	s_mov_b64 s[10:11], s[18:19]
	s_mov_b64 s[26:27], s[16:17]
	s_waitcnt vmcnt(1)
	ds_write_b128 v203, v[98:101]
	s_waitcnt vmcnt(0)
	ds_write_b128 v34, v[102:105] offset:32768
	ds_write_b128 v203, v[106:109] offset:8192
	ds_write_b128 v34, v[110:113] offset:40960
	s_waitcnt lgkmcnt(0)
	s_barrier
	s_cbranch_scc1 .LBB0_1544
	s_add_u32 s6, s37, s24
	s_addc_u32 s7, s38, s25
	s_add_u32 s26, s6, 0xa004000
	s_addc_u32 s27, s7, 0
	s_add_u32 s10, s6, 0xa804000
	s_addc_u32 s11, s7, 0
	s_add_u32 s8, s6, 0xa006000
	s_addc_u32 s9, s7, 0
	s_add_u32 s6, s6, 0xa806000
	s_addc_u32 s7, s7, 0

; #define LAS __attribute__((address_space(3)))
; template <bool FIXED> __device__ __forceinline__ void attn_prompt_unit(const Params& P, const Ctx& C, int bg, int qb) {
;     ...
;         for (int jp = j0; jp <= jl; jp += 2) {
;             LAS unsigned char* kcur = KB + ((jp >> 1) & 1) * 16384; LAS unsigned char* vcur = VB + ((jp >> 1) & 1) * 16384;
;             tile_st(kcur, vcur, wave, lane, kr, vr); tile_st(kcur + 8192, vcur + 8192, wave, lane, kr2, vr2);
;             __syncthreads();
;             if (jp + 2 <= jl) { tile_ld(kb_ + (size_t)(jp + 2) * 4096, vb_ + (size_t)(jp + 2) * 4096, wave, lane, kr, vr); tile_ld(kb_ + (size_t)(jp + 3) * 4096, vb_ + (size_t)(jp + 3) * 4096, wave, lane, kr2, vr2); }
.LBB0_1583:
	s_and_b32 s2, s14, 0x4000
	s_add_i32 s6, s2, 0
	s_add_i32 s2, s6, s44
	s_add_i32 s15, s64, 2
	s_cmp_gt_i32 s15, s31
	v_add_u32_e32 v34, s2, v173
	v_add_u32_e32 v203, s2, v202
	s_cselect_b64 s[2:3], -1, 0
	s_and_b64 vcc, exec, s[2:3]
	s_waitcnt vmcnt(3)
	ds_write_b128 v203, v[98:101]
	s_waitcnt vmcnt(2)
	ds_write_b128 v34, v[102:105] offset:32768
	s_waitcnt vmcnt(1)
	ds_write_b128 v203, v[106:109] offset:8192
	s_waitcnt vmcnt(0)
	ds_write_b128 v34, v[110:113] offset:40960
	s_waitcnt lgkmcnt(0)
	s_barrier
	s_cbranch_vccnz .LBB0_1585
	s_add_i32 s16, s64, 3
	s_ashr_i32 s17, s16, 31
	s_lshl_b64 s[16:17], s[16:17], 13
	v_lshl_add_u64 v[34:35], v[176:177], 0, s[16:17]
	global_load_dwordx4 v[98:101], v[182:183], off
	global_load_dwordx4 v[102:105], v[180:181], off
	v_lshl_add_u64 v[36:37], v[178:179], 0, s[16:17]
	global_load_dwordx4 v[106:109], v[34:35], off
	global_load_dwordx4 v[110:113], v[36:37], off
